# P7 XN/MIXB loads default policy instead of nt, on top of v102
# speedup vs baseline: 1.0073x; 1.0040x over previous
.LBB0_807:
	s_ashr_i32 s7, s6, 31
	s_lshl_b64 s[0:1], s[6:7], 6
	s_waitcnt lgkmcnt(0)
	v_lshl_add_u64 v[16:17], v[24:25], 0, s[0:1]
	global_load_dwordx4 v[30:33], v[16:17], off
	s_add_i32 s12, s3, s6
	s_cmp_lt_i32 s12, 0x8000
	s_cselect_b32 s0, s12, s6
	s_ashr_i32 s1, s0, 31
	s_lshl_b64 s[20:21], s[0:1], 6
	s_lshl_b64 s[14:15], s[0:1], 11
	s_lshl_b64 s[0:1], s[0:1], 2
	s_add_u32 s16, s30, s0
	s_addc_u32 s17, s31, s1
	s_lshl_b64 s[0:1], s[6:7], 11
	v_lshl_add_u64 v[28:29], v[22:23], 0, s[0:1]
	global_load_dwordx2 v[34:35], v[28:29], off offset:1536
	v_lshl_add_u64 v[16:17], v[26:27], 0, s[0:1]
	s_lshl_b64 s[0:1], s[6:7], 2
	s_add_u32 s0, s30, s0
	s_addc_u32 s1, s31, s1
	global_load_dwordx2 v[36:37], v[16:17], off offset:512
	global_load_dwordx2 v[38:39], v[28:29], off offset:512
	global_load_dwordx2 v[40:41], v[16:17], off offset:1024
	global_load_dwordx2 v[42:43], v[28:29], off offset:1024
	global_load_dwordx2 v[44:45], v[16:17], off offset:1536
	global_load_dwordx2 v[46:47], v[28:29], off
	global_load_dwordx2 v[56:57], v[16:17], off
	global_load_dword v58, v21, s[0:1]
	v_lshl_add_u64 v[16:17], v[24:25], 0, s[20:21]
	global_load_dwordx4 v[16:19], v[16:17], off
	s_cmpk_gt_i32 s12, 0x7fff
	s_waitcnt vmcnt(10)
	v_mov_b32_e32 v60, v31
	v_mov_b32_e32 v61, v32
	v_mov_b32_e32 v31, v33
	v_pk_add_f32 v[30:31], v[60:61], v[30:31]
	s_waitcnt vmcnt(8)
	v_and_b32_e32 v61, 0xffff0000, v36
	v_add_f32_e32 v30, v30, v31
	ds_bpermute_b32 v32, v20, v30
	v_and_b32_e32 v55, 0xffff0000, v35
	v_lshlrev_b32_e32 v59, 16, v35
	s_waitcnt vmcnt(4)
	v_lshlrev_b32_e32 v70, 16, v44
	v_and_b32_e32 v72, 0xffff0000, v44
	s_waitcnt lgkmcnt(0)
	v_add_f32_e32 v30, v30, v32
	ds_bpermute_b32 v32, v48, v30
	v_lshlrev_b32_e32 v74, 16, v45
	v_and_b32_e32 v76, 0xffff0000, v45
	s_waitcnt vmcnt(2)
	v_lshlrev_b32_e32 v44, 16, v57
	v_and_b32_e32 v45, 0xffff0000, v57
	s_waitcnt lgkmcnt(0)
	v_add_f32_e32 v30, v30, v32
	v_fmamk_f32 v30, v30, 0x3a800000, v53
	v_mul_f32_e32 v32, 0x4f800000, v30
	v_cmp_gt_f32_e32 vcc, s19, v30
	s_waitcnt vmcnt(1)
	v_mul_f32_e32 v57, v58, v55
	v_and_b32_e32 v31, 0xffff0000, v34
	v_cndmask_b32_e32 v30, v30, v32, vcc
	v_sqrt_f32_e32 v32, v30
	v_lshlrev_b32_e32 v33, 16, v34
	v_lshlrev_b32_e32 v35, 16, v36
	v_lshlrev_b32_e32 v34, 16, v38
	v_add_u32_e32 v55, -1, v32
	v_and_b32_e32 v60, 0xffff0000, v38
	v_lshlrev_b32_e32 v62, 16, v39
	v_and_b32_e32 v36, 0xffff0000, v39
	v_lshlrev_b32_e32 v39, 16, v40
	v_lshlrev_b32_e32 v38, 16, v42
	v_and_b32_e32 v65, 0xffff0000, v40
	v_and_b32_e32 v64, 0xffff0000, v42
	v_lshlrev_b32_e32 v66, 16, v43
	v_and_b32_e32 v40, 0xffff0000, v43
	v_lshlrev_b32_e32 v42, 16, v47
	v_and_b32_e32 v43, 0xffff0000, v47
	v_lshlrev_b32_e32 v68, 16, v46
	v_and_b32_e32 v69, 0xffff0000, v46
	v_lshlrev_b32_e32 v46, 16, v56
	v_and_b32_e32 v47, 0xffff0000, v56
	v_mul_f32_e32 v71, v58, v59
	v_add_u32_e32 v56, 1, v32
	v_fma_f32 v59, -v55, v32, v30
	v_fma_f32 v73, -v56, v32, v30
	v_cmp_ge_f32_e64 s[0:1], 0, v59
	v_lshlrev_b32_e32 v63, 16, v37
	v_and_b32_e32 v37, 0xffff0000, v37
	v_cndmask_b32_e64 v32, v32, v55, s[0:1]
	v_cmp_lt_f32_e64 s[0:1], 0, v73
	v_lshlrev_b32_e32 v67, 16, v41
	v_and_b32_e32 v41, 0xffff0000, v41
	v_cndmask_b32_e64 v32, v32, v56, s[0:1]
	v_mul_f32_e32 v55, 0x37800000, v32
	v_cndmask_b32_e32 v32, v32, v55, vcc
	v_cmp_class_f32_e32 vcc, v30, v54
	v_mov_b32_e32 v73, v58
	s_waitcnt vmcnt(0)
	v_add_f32_e32 v16, v16, v17
	v_cndmask_b32_e32 v30, v32, v30, vcc
	v_div_scale_f32 v32, s[0:1], v30, v30, 1.0
	v_rcp_f32_e32 v55, v32
	v_div_scale_f32 v56, vcc, 1.0, v30, 1.0
	v_add_f32_e32 v18, v18, v19
	v_fma_f32 v59, -v32, v55, 1.0
	v_fmac_f32_e32 v55, v59, v55
	v_mul_f32_e32 v59, v56, v55
	v_fma_f32 v75, -v32, v59, v56
	v_fmac_f32_e32 v59, v75, v55
	v_fma_f32 v32, -v32, v59, v56
	v_div_fmas_f32 v32, v32, v55, v59
	v_div_fixup_f32 v59, v32, v30, 1.0
	v_mov_b32_e32 v30, v59
	v_mul_f32_e32 v32, v59, v74
	v_pk_mul_f32 v[44:45], v[30:31], v[44:45] op_sel_hi:[0,1]
	v_pk_mul_f32 v[34:35], v[58:59], v[34:35]
	v_pk_mul_f32 v[60:61], v[58:59], v[60:61]
	v_pk_mul_f32 v[62:63], v[58:59], v[62:63]
	v_pk_mul_f32 v[36:37], v[58:59], v[36:37]
	v_pk_mul_f32 v[38:39], v[58:59], v[38:39]
	v_pk_mul_f32 v[64:65], v[58:59], v[64:65]
	v_pk_mul_f32 v[66:67], v[58:59], v[66:67]
	v_pk_mul_f32 v[40:41], v[58:59], v[40:41]
	v_mul_f32_e32 v75, v59, v70
	v_mul_f32_e32 v77, v59, v72
	v_mul_f32_e32 v55, v59, v76
	v_mul_f32_e32 v59, v2, v32
	v_pk_mul_f32 v[46:47], v[30:31], v[46:47] op_sel_hi:[0,1]
	v_pk_mul_f32 v[44:45], v[14:15], v[44:45]
	v_pk_mul_f32 v[46:47], v[12:13], v[46:47]
	v_pk_fma_f32 v[80:81], v[58:59], v[42:43], v[44:45] op_sel_hi:[0,1,1]
	v_pk_fma_f32 v[68:69], v[58:59], v[68:69], v[46:47] op_sel_hi:[0,1,1]
	v_pk_mov_b32 v[42:43], v[80:81], v[0:1] op_sel:[1,0]
	v_mov_b32_e32 v74, v81
	v_pk_mul_f32 v[42:43], v[42:43], v[74:75]
	v_pk_mov_b32 v[82:83], v[68:69], v[0:1] op_sel:[1,0]
	v_mov_b32_e32 v74, v69
	v_mov_b32_e32 v72, v80
	v_mov_b32_e32 v32, v80
	v_mov_b32_e32 v44, v68
	v_mov_b32_e32 v45, v58
	v_mov_b32_e32 v46, v68
	v_mov_b32_e32 v47, v33
	v_pk_mul_f32 v[74:75], v[82:83], v[74:75]
	v_pk_fma_f32 v[32:33], v[72:73], v[32:33], v[42:43]
	v_pk_fma_f32 v[72:73], v[44:45], v[46:47], v[74:75]
	v_mul_f32_e32 v79, v3, v55
	v_pk_add_f32 v[42:43], v[72:73], v[32:33]
	v_pk_mul_f32 v[32:33], v[72:73], v[32:33]
	v_add_f32_e32 v16, v16, v18
	v_mov_b32_e32 v43, v33
	v_mov_b32_e32 v32, v63
	v_mov_b32_e32 v33, v37
	v_mov_b32_e32 v63, v36
	v_mov_b32_e32 v36, v35
	v_mov_b32_e32 v37, v61
	v_mov_b32_e32 v35, v60
	v_pk_fma_f32 v[60:61], v[8:9], v[36:37], v[34:35]
	v_pk_fma_f32 v[62:63], v[10:11], v[32:33], v[62:63]
	v_mov_b32_e32 v36, v61
	v_mov_b32_e32 v37, v1
	v_mov_b32_e32 v76, v61
	v_mov_b32_e32 v32, v63
	v_mov_b32_e32 v33, v1
	v_mov_b32_e32 v34, v60
	v_mov_b32_e32 v35, v58
	v_mov_b32_e32 v30, v60
	v_pk_mul_f32 v[36:37], v[36:37], v[76:77]
	v_mov_b32_e32 v76, v63
	v_pk_fma_f32 v[74:75], v[34:35], v[30:31], v[36:37]
	v_mov_b32_e32 v34, v62
	v_mov_b32_e32 v30, v62
	v_pk_mul_f32 v[32:33], v[32:33], v[76:77]
	ds_bpermute_b32 v18, v20, v16
	v_pk_fma_f32 v[30:31], v[34:35], v[30:31], v[32:33]
	s_waitcnt lgkmcnt(0)
	v_add_f32_e32 v16, v16, v18
	v_pk_add_f32 v[32:33], v[74:75], v[30:31]
	v_pk_mul_f32 v[30:31], v[74:75], v[30:31]
	v_mov_b32_e32 v74, v73
	v_mov_b32_e32 v33, v31
	v_pk_add_f32 v[30:31], v[42:43], v[32:33]
	v_mov_b32_e32 v32, v67
	v_mov_b32_e32 v33, v41
	v_mov_b32_e32 v67, v40
	v_pk_fma_f32 v[66:67], v[6:7], v[32:33], v[66:67]
	s_nop 0
	v_mov_b32_e32 v78, v66
	v_mov_b32_e32 v56, v66
	v_pk_add_f32 v[56:57], v[78:79], v[56:57]
	v_mul_f32_e32 v32, v67, v67
	v_pk_fma_f32 v[32:33], v[66:67], v[66:67], v[32:33] op_sel_hi:[1,1,0]
	v_pk_mul_f32 v[34:35], v[56:57], v[56:57]
	s_nop 0
	v_mov_b32_e32 v33, v35
	v_mov_b32_e32 v34, v39
	v_mov_b32_e32 v35, v65
	v_mov_b32_e32 v39, v64
	v_pk_fma_f32 v[64:65], v[4:5], v[34:35], v[38:39]
	s_nop 0
	v_mov_b32_e32 v58, v64
	v_mov_b32_e32 v70, v64
	v_pk_add_f32 v[58:59], v[58:59], v[70:71]
	v_mul_f32_e32 v34, v65, v65
	v_pk_fma_f32 v[34:35], v[64:65], v[64:65], v[34:35] op_sel_hi:[1,1,0]
	v_pk_mul_f32 v[36:37], v[58:59], v[58:59]
	v_lshl_add_u64 v[70:71], v[26:27], 0, s[14:15]
	v_mov_b32_e32 v35, v37
	v_pk_add_f32 v[32:33], v[34:35], v[32:33]
	v_lshl_add_u64 v[34:35], v[22:23], 0, s[14:15]
	v_pk_add_f32 v[30:31], v[30:31], v[32:33]
	s_nop 0
	v_add_f32_e32 v31, v30, v31
	ds_bpermute_b32 v32, v20, v31
	global_load_dword v30, v21, s[16:17]
	s_waitcnt lgkmcnt(0)
	v_add_f32_e32 v31, v31, v32
	ds_bpermute_b32 v36, v48, v31
	global_load_dwordx2 v[32:33], v[34:35], off
	global_load_dwordx2 v[42:43], v[34:35], off offset:512
	global_load_dwordx2 v[38:39], v[34:35], off offset:1024
	global_load_dwordx2 v[46:47], v[34:35], off offset:1536
	s_waitcnt lgkmcnt(0)
	v_add_f32_e32 v31, v31, v36
	global_load_dwordx2 v[34:35], v[70:71], off
	global_load_dwordx2 v[44:45], v[70:71], off offset:512
	global_load_dwordx2 v[40:41], v[70:71], off offset:1024
	global_load_dwordx2 v[36:37], v[70:71], off offset:1536
	ds_bpermute_b32 v55, v49, v31
	s_waitcnt lgkmcnt(0)
	v_add_f32_e32 v31, v31, v55
	ds_bpermute_b32 v55, v50, v31
	s_waitcnt lgkmcnt(0)
	v_add_f32_e32 v31, v31, v55
	ds_bpermute_b32 v55, v51, v31
	s_waitcnt lgkmcnt(0)
	v_add_f32_e32 v31, v31, v55
	ds_bpermute_b32 v55, v52, v31
	s_waitcnt lgkmcnt(0)
	v_add_f32_e32 v17, v31, v55
	v_fmamk_f32 v17, v17, 0x3a800000, v53
	v_mul_f32_e32 v31, 0x4f800000, v17
	v_cmp_gt_f32_e32 vcc, s19, v17
	s_nop 1
	v_cndmask_b32_e32 v17, v17, v31, vcc
	v_sqrt_f32_e32 v31, v17
	s_nop 0
	v_add_u32_e32 v19, -1, v31
	v_fma_f32 v55, -v19, v31, v17
	v_cmp_ge_f32_e64 s[0:1], 0, v55
	v_add_u32_e32 v55, 1, v31
	s_nop 0
	v_cndmask_b32_e64 v19, v31, v19, s[0:1]
	v_fma_f32 v31, -v55, v31, v17
	v_cmp_lt_f32_e64 s[0:1], 0, v31
	s_nop 1
	v_cndmask_b32_e64 v19, v19, v55, s[0:1]
	v_mul_f32_e32 v31, 0x37800000, v19
	v_cndmask_b32_e32 v19, v19, v31, vcc
	v_cmp_class_f32_e32 vcc, v17, v54
	s_nop 1
	v_cndmask_b32_e32 v19, v19, v17, vcc
	v_div_scale_f32 v31, s[0:1], v19, v19, 1.0
	v_rcp_f32_e32 v55, v31
	ds_bpermute_b32 v17, v48, v16
	v_fma_f32 v18, -v31, v55, 1.0
	v_fmac_f32_e32 v55, v18, v55
	v_div_scale_f32 v18, vcc, 1.0, v19, 1.0
	v_mul_f32_e32 v56, v18, v55
	v_fma_f32 v58, -v31, v56, v18
	v_fmac_f32_e32 v56, v58, v55
	v_fma_f32 v18, -v31, v56, v18
	v_div_fmas_f32 v18, v18, v55, v56
	v_div_fixup_f32 v18, v18, v19, 1.0
	v_pk_mul_f32 v[60:61], v[18:19], v[60:61] op_sel_hi:[0,1]
	v_pk_mul_f32 v[62:63], v[18:19], v[62:63] op_sel_hi:[0,1]
	v_cvt_pk_bf16_f32 v60, v60, v61
	v_cvt_pk_bf16_f32 v61, v62, v63
	global_store_dwordx2 v[28:29], v[60:61], off offset:512 sc1
	v_pk_mul_f32 v[60:61], v[18:19], v[64:65] op_sel_hi:[0,1]
	v_pk_mul_f32 v[62:63], v[18:19], v[66:67] op_sel_hi:[0,1]
	v_cvt_pk_bf16_f32 v60, v60, v61
	v_cvt_pk_bf16_f32 v61, v62, v63
	v_mov_b32_e32 v56, v59
	v_pk_mul_f32 v[68:69], v[18:19], v[68:69] op_sel_hi:[0,1]
	v_pk_mul_f32 v[70:71], v[18:19], v[80:81] op_sel_hi:[0,1]
	global_store_dwordx2 v[28:29], v[60:61], off offset:1024 sc1
	v_pk_mul_f32 v[60:61], v[18:19], v[74:75] op_sel_hi:[0,1]
	v_pk_mul_f32 v[18:19], v[18:19], v[56:57] op_sel_hi:[0,1]
	v_cvt_pk_bf16_f32 v68, v68, v69
	v_cvt_pk_bf16_f32 v69, v70, v71
	v_cvt_pk_bf16_f32 v58, v60, v61
	v_cvt_pk_bf16_f32 v59, v18, v19
	global_store_dwordx2 v[28:29], v[68:69], off sc1
	global_store_dwordx2 v[28:29], v[58:59], off offset:1536 sc1
	s_cbranch_scc1 .LBB0_806
	s_waitcnt lgkmcnt(0)
	v_add_f32_e32 v16, v16, v17
	v_fmamk_f32 v16, v16, 0x3a800000, v53
	v_mul_f32_e32 v17, 0x4f800000, v16
	v_cmp_gt_f32_e32 vcc, s19, v16
	s_waitcnt vmcnt(8)
	v_lshlrev_b32_e32 v19, 16, v47
	s_waitcnt vmcnt(6)
	v_lshlrev_b32_e32 v57, 16, v44
	v_cndmask_b32_e32 v16, v16, v17, vcc
	v_sqrt_f32_e32 v18, v16
	v_and_b32_e32 v17, 0xffff0000, v47
	v_lshlrev_b32_e32 v47, 16, v46
	v_and_b32_e32 v59, 0xffff0000, v44
	v_add_u32_e32 v28, -1, v18
	v_fma_f32 v29, -v28, v18, v16
	v_cmp_ge_f32_e64 s[0:1], 0, v29
	v_add_u32_e32 v29, 1, v18
	v_lshlrev_b32_e32 v61, 16, v45
	v_cndmask_b32_e64 v28, v18, v28, s[0:1]
	v_fma_f32 v18, -v29, v18, v16
	v_cmp_lt_f32_e64 s[0:1], 0, v18
	v_and_b32_e32 v45, 0xffff0000, v45
	v_and_b32_e32 v44, 0xffff0000, v43
	v_cndmask_b32_e64 v18, v28, v29, s[0:1]
	v_mul_f32_e32 v28, 0x37800000, v18
	v_cndmask_b32_e32 v18, v18, v28, vcc
	v_cmp_class_f32_e32 vcc, v16, v54
	v_and_b32_e32 v29, 0xffff0000, v46
	v_lshlrev_b32_e32 v56, 16, v42
	v_cndmask_b32_e32 v16, v18, v16, vcc
	v_div_scale_f32 v18, s[0:1], v16, v16, 1.0
	v_rcp_f32_e32 v28, v18
	v_and_b32_e32 v58, 0xffff0000, v42
	v_lshlrev_b32_e32 v60, 16, v43
	s_waitcnt vmcnt(5)
	v_and_b32_e32 v63, 0xffff0000, v40
	v_fma_f32 v31, -v18, v28, 1.0
	v_fmac_f32_e32 v28, v31, v28
	v_div_scale_f32 v31, vcc, 1.0, v16, 1.0
	v_mul_f32_e32 v46, v31, v28
	v_fma_f32 v55, -v18, v46, v31
	v_fmac_f32_e32 v46, v55, v28
	v_fma_f32 v18, -v18, v46, v31
	v_div_fmas_f32 v18, v18, v28, v46
	v_div_fixup_f32 v31, v18, v16, 1.0
	v_pk_mul_f32 v[42:43], v[30:31], v[44:45]
	v_lshlrev_b32_e32 v45, 16, v40
	v_lshlrev_b32_e32 v65, 16, v41
	v_and_b32_e32 v41, 0xffff0000, v41
	v_and_b32_e32 v40, 0xffff0000, v39
	s_waitcnt vmcnt(4)
	v_lshlrev_b32_e32 v16, 16, v36
	v_lshlrev_b32_e32 v44, 16, v38
	v_and_b32_e32 v62, 0xffff0000, v38
	v_lshlrev_b32_e32 v64, 16, v39
	v_pk_mul_f32 v[38:39], v[30:31], v[40:41]
	v_mul_f32_e32 v41, v31, v16
	v_and_b32_e32 v16, 0xffff0000, v36
	v_mul_f32_e32 v67, v31, v16
	v_lshlrev_b32_e32 v16, 16, v37
	v_mul_f32_e32 v16, v31, v16
	v_mul_f32_e32 v69, v2, v16
	v_and_b32_e32 v16, 0xffff0000, v37
	v_mul_f32_e32 v16, v31, v16
	v_mul_f32_e32 v17, v30, v17
	v_mul_f32_e32 v37, v3, v16
	v_lshlrev_b32_e32 v72, 16, v35
	v_and_b32_e32 v73, 0xffff0000, v35
	v_mov_b32_e32 v16, v31
	v_pk_mul_f32 v[72:73], v[16:17], v[72:73] op_sel_hi:[0,1]
	v_lshlrev_b32_e32 v70, 16, v33
	v_and_b32_e32 v71, 0xffff0000, v33
	v_pk_mul_f32 v[72:73], v[14:15], v[72:73]
	v_and_b32_e32 v33, 0xffff0000, v34
	v_pk_fma_f32 v[70:71], v[30:31], v[70:71], v[72:73] op_sel_hi:[0,1,1]
	v_lshlrev_b32_e32 v72, 16, v32
	v_and_b32_e32 v73, 0xffff0000, v32
	v_lshlrev_b32_e32 v32, 16, v34
	v_pk_mul_f32 v[32:33], v[16:17], v[32:33] op_sel_hi:[0,1]
	v_pk_mul_f32 v[32:33], v[12:13], v[32:33]
	v_mov_b32_e32 v40, v71
	v_pk_fma_f32 v[32:33], v[30:31], v[72:73], v[32:33] op_sel_hi:[0,1,1]
	v_pk_mov_b32 v[72:73], v[70:71], v[0:1] op_sel:[1,0]
	v_pk_mov_b32 v[78:79], v[32:33], v[0:1] op_sel:[1,0]
	v_pk_mul_f32 v[72:73], v[72:73], v[40:41]
	v_mov_b32_e32 v40, v33
	v_mov_b32_e32 v34, v70
	v_mov_b32_e32 v35, v30
	v_mov_b32_e32 v46, v70
	v_mov_b32_e32 v74, v32
	v_mov_b32_e32 v75, v30
	v_mov_b32_e32 v76, v32
	v_mov_b32_e32 v77, v47
	v_pk_mul_f32 v[40:41], v[78:79], v[40:41]
	v_pk_fma_f32 v[34:35], v[34:35], v[46:47], v[72:73]
	v_pk_fma_f32 v[40:41], v[74:75], v[76:77], v[40:41]
	v_pk_mul_f32 v[60:61], v[30:31], v[60:61]
	v_pk_add_f32 v[46:47], v[40:41], v[34:35]
	v_pk_mul_f32 v[34:35], v[40:41], v[34:35]
	v_pk_mul_f32 v[56:57], v[30:31], v[56:57]
	v_pk_mul_f32 v[58:59], v[30:31], v[58:59]
	v_mov_b32_e32 v47, v35
	v_mov_b32_e32 v34, v61
	v_mov_b32_e32 v35, v43
	v_mov_b32_e32 v61, v42
	v_pk_fma_f32 v[34:35], v[10:11], v[34:35], v[60:61]
	v_mov_b32_e32 v60, v57
	v_mov_b32_e32 v61, v59
	v_mov_b32_e32 v57, v58
	v_pk_fma_f32 v[56:57], v[8:9], v[60:61], v[56:57]
	v_mov_b32_e32 v61, v1
	v_mov_b32_e32 v60, v57
	v_mov_b32_e32 v66, v57
	v_mov_b32_e32 v42, v35
	v_mov_b32_e32 v43, v1
	v_mov_b32_e32 v58, v56
	v_mov_b32_e32 v59, v30
	v_mov_b32_e32 v28, v56
	v_pk_mul_f32 v[60:61], v[60:61], v[66:67]
	v_mov_b32_e32 v66, v35
	v_mul_f32_e32 v19, v30, v19
	v_pk_mul_f32 v[44:45], v[30:31], v[44:45]
	v_pk_mul_f32 v[62:63], v[30:31], v[62:63]
	v_pk_mul_f32 v[64:65], v[30:31], v[64:65]
	v_pk_fma_f32 v[58:59], v[58:59], v[28:29], v[60:61]
	v_mov_b32_e32 v60, v34
	v_mov_b32_e32 v61, v30
	v_mov_b32_e32 v28, v34
	v_pk_mul_f32 v[30:31], v[42:43], v[66:67]
	s_ashr_i32 s13, s12, 31
	v_pk_fma_f32 v[28:29], v[60:61], v[28:29], v[30:31]
	s_nop 0
	v_pk_add_f32 v[30:31], v[58:59], v[28:29]
	v_pk_mul_f32 v[28:29], v[58:59], v[28:29]
	v_mov_b32_e32 v58, v41
	v_mov_b32_e32 v31, v29
	v_pk_add_f32 v[28:29], v[46:47], v[30:31]
	v_mov_b32_e32 v30, v65
	v_mov_b32_e32 v31, v39
	v_mov_b32_e32 v65, v38
	v_pk_fma_f32 v[30:31], v[6:7], v[30:31], v[64:65]
	s_nop 0
	v_mov_b32_e32 v36, v30
	v_mov_b32_e32 v16, v30
	v_pk_add_f32 v[16:17], v[36:37], v[16:17]
	v_mul_f32_e32 v18, v31, v31
	v_pk_fma_f32 v[36:37], v[30:31], v[30:31], v[18:19] op_sel_hi:[1,1,0]
	v_pk_mul_f32 v[38:39], v[16:17], v[16:17]
	s_nop 0
	v_mov_b32_e32 v37, v39
	v_mov_b32_e32 v38, v45
	v_mov_b32_e32 v39, v63
	v_mov_b32_e32 v45, v62
	v_pk_fma_f32 v[38:39], v[4:5], v[38:39], v[44:45]
	s_nop 0
	v_mov_b32_e32 v68, v38
	v_mov_b32_e32 v18, v38
	v_pk_add_f32 v[18:19], v[68:69], v[18:19]
	v_mul_f32_e32 v16, v39, v39
	v_pk_fma_f32 v[42:43], v[38:39], v[38:39], v[16:17] op_sel_hi:[1,1,0]
	v_pk_mul_f32 v[44:45], v[18:19], v[18:19]
	s_nop 0
	v_mov_b32_e32 v43, v45
	v_pk_add_f32 v[36:37], v[42:43], v[36:37]
	s_nop 0
	v_pk_add_f32 v[28:29], v[28:29], v[36:37]
	s_nop 0
	v_add_f32_e32 v16, v28, v29
	ds_bpermute_b32 v18, v20, v16
	s_waitcnt lgkmcnt(0)
	v_add_f32_e32 v16, v16, v18
	ds_bpermute_b32 v18, v48, v16
	s_waitcnt lgkmcnt(0)
	v_add_f32_e32 v16, v16, v18
	ds_bpermute_b32 v18, v49, v16
	s_waitcnt lgkmcnt(0)
	v_add_f32_e32 v16, v16, v18
	ds_bpermute_b32 v18, v50, v16
	s_waitcnt lgkmcnt(0)
	v_add_f32_e32 v16, v16, v18
	ds_bpermute_b32 v18, v51, v16
	s_waitcnt lgkmcnt(0)
	v_add_f32_e32 v16, v16, v18
	ds_bpermute_b32 v18, v52, v16
	s_waitcnt lgkmcnt(0)
	v_add_f32_e32 v16, v16, v18
	v_fmamk_f32 v16, v16, 0x3a800000, v53
	v_mul_f32_e32 v18, 0x4f800000, v16
	v_cmp_gt_f32_e32 vcc, s19, v16
	s_nop 1
	v_cndmask_b32_e32 v16, v16, v18, vcc
	v_sqrt_f32_e32 v18, v16
	s_nop 0
	v_add_u32_e32 v28, -1, v18
	v_fma_f32 v29, -v28, v18, v16
	v_cmp_ge_f32_e64 s[0:1], 0, v29
	v_add_u32_e32 v29, 1, v18
	s_nop 0
	v_cndmask_b32_e64 v28, v18, v28, s[0:1]
	v_fma_f32 v18, -v29, v18, v16
	v_cmp_lt_f32_e64 s[0:1], 0, v18
	s_nop 1
	v_cndmask_b32_e64 v18, v28, v29, s[0:1]
	v_mul_f32_e32 v28, 0x37800000, v18
	v_cndmask_b32_e32 v18, v18, v28, vcc
	v_cmp_class_f32_e32 vcc, v16, v54
	s_nop 1
	v_cndmask_b32_e32 v16, v18, v16, vcc
	v_div_scale_f32 v18, s[0:1], v16, v16, 1.0
	v_rcp_f32_e32 v36, v18
	s_lshl_b64 s[0:1], s[12:13], 11
	v_lshl_add_u64 v[28:29], v[22:23], 0, s[0:1]
	v_fma_f32 v37, -v18, v36, 1.0
	v_fmac_f32_e32 v36, v37, v36
	v_div_scale_f32 v37, vcc, 1.0, v16, 1.0
	v_mul_f32_e32 v40, v37, v36
	v_fma_f32 v42, -v18, v40, v37
	v_fmac_f32_e32 v40, v42, v36
	v_fma_f32 v18, -v18, v40, v37
	v_div_fmas_f32 v18, v18, v36, v40
	v_div_fixup_f32 v18, v18, v16, 1.0
	v_pk_mul_f32 v[32:33], v[18:19], v[32:33] op_sel_hi:[0,1]
	v_pk_mul_f32 v[36:37], v[18:19], v[70:71] op_sel_hi:[0,1]
	v_cvt_pk_bf16_f32 v32, v32, v33
	v_cvt_pk_bf16_f32 v33, v36, v37
	global_store_dwordx2 v[28:29], v[32:33], off sc1
	v_pk_mul_f32 v[32:33], v[18:19], v[56:57] op_sel_hi:[0,1]
	v_pk_mul_f32 v[34:35], v[18:19], v[34:35] op_sel_hi:[0,1]
	v_cvt_pk_bf16_f32 v32, v32, v33
	v_cvt_pk_bf16_f32 v33, v34, v35
	global_store_dwordx2 v[28:29], v[32:33], off offset:512 sc1
	v_pk_mul_f32 v[32:33], v[18:19], v[38:39] op_sel_hi:[0,1]
	v_pk_mul_f32 v[30:31], v[18:19], v[30:31] op_sel_hi:[0,1]
	v_mov_b32_e32 v16, v19
	v_cvt_pk_bf16_f32 v32, v32, v33
	v_cvt_pk_bf16_f32 v33, v30, v31
	v_pk_mul_f32 v[30:31], v[18:19], v[58:59] op_sel_hi:[0,1]
	v_pk_mul_f32 v[16:17], v[18:19], v[16:17] op_sel_hi:[0,1]
	v_cvt_pk_bf16_f32 v30, v30, v31
	v_cvt_pk_bf16_f32 v31, v16, v17
	global_store_dwordx2 v[28:29], v[32:33], off offset:1024 sc1
	global_store_dwordx2 v[28:29], v[30:31], off offset:1536 sc1
	s_branch .LBB0_806
